# mixer-output phase loads issued up front (RWKV and GLA parts), rope loads hoisted in prep
# speedup vs baseline: 1.0191x; 1.0091x over previous
; __device__ __forceinline__ unsigned pk2(float lo, float hi) { const f32x2 v = {lo, hi}; return __builtin_bit_cast(unsigned, __builtin_convertvector(v, bf2n_t_)); }
; __device__ __forceinline__ void phase_prep(const Frame& F, ArgsRef A, int l) {
;     ...
;         for (int m = gw; m < ML; m += NGW) {
;             const int t = m & (SEQ - 1);
;             const float pos = axis == 0 ? (float)(t >> 6) : (float)(t & 63);
;             const float a0 = pos * invf0, a1 = pos * invf1; const float sn0 = __sinf(a0), cs0 = __cosf(a0), sn1 = __sinf(a1), cs1 = __cosf(a1);
;             const bf16* zr = ZA + (size_t)m * ZA_LD + hs * 128 + axis * 64 + f2;
; #pragma unroll
;             for (int hp = 0; hp < 5; ++hp) {
;                 const unsigned w1 = *(const unsigned*)(zr + hp * 256), w2 = *(const unsigned*)(zr + hp * 256 + 32);
;                 const float x10 = bflo(w1), x11 = bfhi(w1), x20 = bflo(w2), x21 = bfhi(w2);
;                 const unsigned o1 = pk2(x10 * cs0 - x20 * sn0, x11 * cs1 - x21 * sn1), o2 = pk2(x20 * cs0 + x10 * sn0, x21 * cs1 + x11 * sn1);
;                 const int hh = 2 * hp + hs;
;                 bf16* dst = hh < 8 ? QR + (size_t)m * 1024 + hh * 128 + axis * 64 + f2 : KR + (size_t)m * 256 + (hh - 8) * 128 + axis * 64 + f2;
;                 *(unsigned*)dst = o1; *(unsigned*)(dst + 32) = o2;
;             }
;         }
.LBB0_538:
	s_bfe_u32 s15, s1, 0x50006
	s_and_b32 s19, s1, 63
	v_mov_b32_e32 v19, s19
	v_mov_b32_e32 v21, s15
	v_cndmask_b32_e32 v19, v19, v21, vcc
	v_cvt_f32_ubyte0_e32 v19, v19
	v_mul_f32_e32 v21, v30, v19
	v_mul_f32_e32 v19, v31, v19
	v_mul_f32_e32 v21, 0.15915494, v21
	v_mul_f32_e32 v19, 0.15915494, v19
	v_lshl_add_u64 v[26:27], s[16:17], 0, v[16:17]
	v_sin_f32_e32 v22, v21
	v_cos_f32_e32 v24, v21
	v_sin_f32_e32 v23, v19
	v_cos_f32_e32 v25, v19
	global_load_dword v19, v[26:27], off offset:-1088
	global_load_dword v21, v[26:27], off offset:-1024
	global_load_dword v100, v[26:27], off offset:-576
	global_load_dword v101, v[26:27], off offset:-512
	global_load_dword v102, v[26:27], off offset:-64
	global_load_dword v103, v[26:27], off
	global_load_dword v104, v[26:27], off offset:448
	global_load_dword v105, v[26:27], off offset:512
	global_load_dword v106, v[26:27], off offset:960
	global_load_dword v107, v[26:27], off offset:1024
	s_mov_b64 s[26:27], 0x44900000
	s_add_i32 s1, s1, s14
	v_lshl_add_u64 v[16:17], v[16:17], 0, s[24:25]
	s_cmpk_gt_i32 s1, 0x3fff
	s_waitcnt vmcnt(8)
	v_lshlrev_b32_e32 v28, 16, v19
	v_lshlrev_b32_e32 v32, 16, v21
	v_and_b32_e32 v33, 0xffff0000, v21
	v_and_b32_e32 v29, 0xffff0000, v19
	v_pk_mul_f32 v[34:35], v[22:23], v[32:33]
	v_pk_mul_f32 v[32:33], v[24:25], v[32:33]
	v_pk_fma_f32 v[34:35], v[24:25], v[28:29], v[34:35] neg_lo:[0,0,1] neg_hi:[0,0,1]
	v_pk_fma_f32 v[28:29], v[22:23], v[28:29], v[32:33]
	v_cvt_pk_bf16_f32 v36, v34, v35
	v_cvt_pk_bf16_f32 v37, v28, v29
	v_lshl_add_u64 v[28:29], s[16:17], 0, v[4:5]
	v_lshl_add_u64 v[32:33], v[28:29], 0, s[26:27]
	v_lshl_add_u64 v[34:35], s[16:17], 0, v[14:15]
	v_cndmask_b32_e64 v33, v35, v33, s[2:3]
	v_cndmask_b32_e64 v32, v34, v32, s[2:3]
	v_mov_b32_e32 v19, v2
	v_lshl_add_u64 v[32:33], v[32:33], 0, v[18:19]
	v_mov_b32_e32 v21, v2
	v_lshl_add_u64 v[32:33], v[32:33], 0, v[20:21]
	global_store_dword v[32:33], v36, off
	global_store_dword v[32:33], v37, off offset:64
	s_nop 0
	s_nop 0
	s_nop 0
	s_mov_b64 s[26:27], 0x44900200
	v_lshl_add_u64 v[4:5], v[4:5], 0, s[12:13]
	v_lshl_add_u64 v[14:15], v[14:15], 0, s[22:23]
	s_waitcnt vmcnt(9)
	v_lshlrev_b32_e32 v32, 16, v100
	s_waitcnt vmcnt(8)
	v_lshlrev_b32_e32 v34, 16, v101
	v_and_b32_e32 v35, 0xffff0000, v101
	v_and_b32_e32 v33, 0xffff0000, v100
	v_pk_mul_f32 v[36:37], v[22:23], v[34:35]
	v_pk_mul_f32 v[34:35], v[24:25], v[34:35]
	v_pk_fma_f32 v[36:37], v[24:25], v[32:33], v[36:37] neg_lo:[0,0,1] neg_hi:[0,0,1]
	v_pk_fma_f32 v[32:33], v[22:23], v[32:33], v[34:35]
	v_cvt_pk_bf16_f32 v36, v36, v37
	v_cvt_pk_bf16_f32 v37, v32, v33
	v_lshl_add_u64 v[32:33], v[28:29], 0, s[26:27]
	v_lshl_add_u64 v[34:35], s[16:17], 0, v[12:13]
	v_cndmask_b32_e64 v33, v35, v33, s[4:5]
	v_cndmask_b32_e64 v32, v34, v32, s[4:5]
	v_lshl_add_u64 v[32:33], v[32:33], 0, v[18:19]
	v_lshl_add_u64 v[32:33], v[32:33], 0, v[20:21]
	global_store_dword v[32:33], v36, off
	global_store_dword v[32:33], v37, off offset:64
	s_nop 0
	s_nop 0
	s_nop 0
	s_mov_b64 s[26:27], 0x44900400
	v_lshl_add_u64 v[12:13], v[12:13], 0, s[22:23]
	s_waitcnt vmcnt(9)
	v_lshlrev_b32_e32 v32, 16, v102
	s_waitcnt vmcnt(8)
	v_lshlrev_b32_e32 v34, 16, v103
	v_and_b32_e32 v35, 0xffff0000, v103
	v_and_b32_e32 v33, 0xffff0000, v102
	v_pk_mul_f32 v[36:37], v[22:23], v[34:35]
	v_pk_mul_f32 v[34:35], v[24:25], v[34:35]
	v_pk_fma_f32 v[36:37], v[24:25], v[32:33], v[36:37] neg_lo:[0,0,1] neg_hi:[0,0,1]
	v_pk_fma_f32 v[32:33], v[22:23], v[32:33], v[34:35]
	v_cvt_pk_bf16_f32 v36, v36, v37
	v_cvt_pk_bf16_f32 v37, v32, v33
	v_lshl_add_u64 v[32:33], v[28:29], 0, s[26:27]
	v_lshl_add_u64 v[34:35], s[16:17], 0, v[10:11]
	v_cndmask_b32_e64 v33, v35, v33, s[6:7]
	v_cndmask_b32_e64 v32, v34, v32, s[6:7]
	v_lshl_add_u64 v[32:33], v[32:33], 0, v[18:19]
	v_lshl_add_u64 v[32:33], v[32:33], 0, v[20:21]
	global_store_dword v[32:33], v36, off
	global_store_dword v[32:33], v37, off offset:64
	s_nop 0
	s_nop 0
	s_nop 0
	s_mov_b64 s[26:27], 0x44900600
	v_lshl_add_u64 v[10:11], v[10:11], 0, s[22:23]
	s_waitcnt vmcnt(9)
	v_lshlrev_b32_e32 v32, 16, v104
	s_waitcnt vmcnt(8)
	v_lshlrev_b32_e32 v34, 16, v105
	v_and_b32_e32 v35, 0xffff0000, v105
	v_and_b32_e32 v33, 0xffff0000, v104
	v_pk_mul_f32 v[36:37], v[22:23], v[34:35]
	v_pk_mul_f32 v[34:35], v[24:25], v[34:35]
	v_pk_fma_f32 v[36:37], v[24:25], v[32:33], v[36:37] neg_lo:[0,0,1] neg_hi:[0,0,1]
	v_pk_fma_f32 v[32:33], v[22:23], v[32:33], v[34:35]
	v_cvt_pk_bf16_f32 v36, v36, v37
	v_cvt_pk_bf16_f32 v37, v32, v33
	v_lshl_add_u64 v[32:33], v[28:29], 0, s[26:27]
	v_lshl_add_u64 v[34:35], s[16:17], 0, v[8:9]
	v_cndmask_b32_e64 v33, v35, v33, s[8:9]
	v_cndmask_b32_e64 v32, v34, v32, s[8:9]
	v_lshl_add_u64 v[32:33], v[32:33], 0, v[18:19]
	v_lshl_add_u64 v[32:33], v[32:33], 0, v[20:21]
	global_store_dword v[32:33], v36, off
	global_store_dword v[32:33], v37, off offset:64
	s_nop 0
	s_nop 0
	s_nop 0
	s_mov_b64 s[26:27], 0x44900800
	v_lshl_add_u64 v[8:9], v[8:9], 0, s[22:23]
	s_waitcnt vmcnt(9)
	v_lshlrev_b32_e32 v26, 16, v106
	v_and_b32_e32 v27, 0xffff0000, v106
	s_waitcnt vmcnt(8)
	v_lshlrev_b32_e32 v32, 16, v107
	v_and_b32_e32 v33, 0xffff0000, v107
	v_pk_mul_f32 v[34:35], v[22:23], v[32:33]
	s_nop 0
	v_pk_fma_f32 v[34:35], v[24:25], v[26:27], v[34:35] neg_lo:[0,0,1] neg_hi:[0,0,1]
	v_pk_mul_f32 v[24:25], v[24:25], v[32:33]
	v_cvt_pk_bf16_f32 v34, v34, v35
	v_pk_fma_f32 v[22:23], v[22:23], v[26:27], v[24:25]
	v_lshl_add_u64 v[24:25], s[16:17], 0, v[6:7]
	v_cvt_pk_bf16_f32 v26, v22, v23
	v_lshl_add_u64 v[22:23], v[28:29], 0, s[26:27]
	v_cndmask_b32_e64 v23, v25, v23, s[10:11]
	v_cndmask_b32_e64 v22, v24, v22, s[10:11]
	v_lshl_add_u64 v[22:23], v[22:23], 0, v[18:19]
	v_lshl_add_u64 v[22:23], v[22:23], 0, v[20:21]
	v_lshl_add_u64 v[6:7], v[6:7], 0, s[22:23]
	global_store_dword v[22:23], v34, off
	global_store_dword v[22:23], v26, off offset:64
	s_cbranch_scc0 .LBB0_538

; __device__ __forceinline__ void phase_mixout(const Frame& F, ArgsRef A, int l, int nrows) {
;     ...
;         for (int m = F.bid * 2 + (F.wave >> 2); m < nrows; m += 2 * F.G) {
;             int idx, len; if (m < ML) { idx = m & (SEQ - 1); len = SEQ; } else { idx = (m - ML) & (CL - 1); len = CL; }
;             const float fl = idx > 0 ? 1.f : 0.f, fr = idx < len - 1 ? 1.f : 0.f;
;             const bf16* z0 = ZR + (size_t)m * ZR_W + 2 * 1024 + c0; const bf16* zl = idx > 0 ? z0 - ZR_W : z0; const bf16* zrr = idx < len - 1 ? z0 + ZR_W : z0;
;             const v2u wc = *(const v2u*)z0, wl = *(const v2u*)zl, wr = *(const v2u*)zrr;
;             const f32x4 xc = (f32x4){bflo(wc.x), bfhi(wc.x), bflo(wc.y), bfhi(wc.y)}, xl = (f32x4){bflo(wl.x), bfhi(wl.x), bflo(wl.y), bfhi(wl.y)}, xr = (f32x4){bflo(wr.x), bfhi(wr.x), bflo(wr.y), bfhi(wr.y)};
;             const f32x4 v = xc * tpv[1] + xl * tpv[0] * fl + xr * tpv[2] * fr;
;             const v2u yw0 = *(const v2u*)(Y + (size_t)m * 1024 + c0), yw1 = *(const v2u*)(Y + ((size_t)MT + m) * 1024 + c0);
;             const f32x4 y0 = (f32x4){bflo(yw0.x), bfhi(yw0.x), bflo(yw0.y), bfhi(yw0.y)}, y1 = (f32x4){bflo(yw1.x), bfhi(yw1.x), bflo(yw1.y), bfhi(yw1.y)};
;             const float bs = BS[(size_t)m * 16 + hd] + BS[((size_t)MT + m) * 16 + hd];
.LBB0_906:
	s_cmpk_lt_i32 s19, 0x4000
	s_cselect_b32 s7, 0x7ff, s37
	s_and_b32 s20, s7, s19
	s_cmp_eq_u32 s20, 0
	s_cselect_b64 s[2:3], -1, 0
	v_cndmask_b32_e64 v30, 1.0, 0, s[2:3]
	s_and_b64 s[2:3], s[2:3], exec
	s_cselect_b32 s2, 0, 0xffffe200
	s_cselect_b32 s3, 0, -1
	s_add_u32 s2, s0, s2
	s_addc_u32 s3, s1, s3
	s_cmp_eq_u32 s20, s7
	s_cselect_b64 s[20:21], -1, 0
	v_lshl_add_u64 v[36:37], s[2:3], 0, v[28:29]
	s_and_b64 s[2:3], s[20:21], exec
	s_cselect_b32 s2, 0, 0x1e00
	s_add_u32 s2, s0, s2
	s_addc_u32 s3, s1, 0
	v_lshl_add_u64 v[34:35], s[0:1], 0, v[28:29]
	v_lshl_add_u64 v[38:39], s[2:3], 0, v[28:29]
	global_load_dwordx2 v[34:35], v[34:35], off
	s_nop 0
	global_load_dwordx2 v[36:37], v[36:37], off
	s_nop 0
	global_load_dwordx2 v[38:39], v[38:39], off
	v_cndmask_b32_e64 v32, 1.0, 0, s[20:21]
	s_mov_b32 s2, 0x22d00000
	s_add_i32 s19, s19, s6
	v_lshl_add_u64 v[28:29], v[28:29], 0, s[14:15]
	s_cmp_ge_i32 s19, s17
	v_lshl_add_u64 v[104:105], s[0:1], 0, v[26:27]
	v_add_co_u32_e32 v106, vcc, s2, v104
	s_mov_b32 s2, 0x25100000
	s_nop 0
	v_addc_co_u32_e32 v107, vcc, 0, v105, vcc
	v_add_co_u32_e32 v108, vcc, s2, v104
	s_mov_b32 s2, 0x2bd00000
	s_nop 0
	v_addc_co_u32_e32 v109, vcc, 0, v105, vcc
	v_add_co_u32_e32 v110, vcc, s2, v104
	v_lshl_add_u64 v[112:113], s[0:1], 0, v[24:25]
	s_mov_b32 s2, 0x56400000
	v_addc_co_u32_e32 v111, vcc, 0, v105, vcc
	v_add_co_u32_e32 v114, vcc, s2, v112
	s_mov_b32 s2, 0x56520000
	s_nop 0
	v_addc_co_u32_e32 v115, vcc, 0, v113, vcc
	v_add_co_u32_e32 v116, vcc, s2, v112
	s_mov_b32 s2, 0x22d00000
	s_nop 0
	v_addc_co_u32_e32 v117, vcc, 0, v113, vcc
	global_load_dwordx2 v[118:119], v[106:107], off
	global_load_dwordx2 v[120:121], v[108:109], off
	global_load_dword v122, v[114:115], off
	global_load_dword v123, v[116:117], off
	global_load_dwordx2 v[124:125], v[110:111], off
	s_waitcnt vmcnt(5)
	v_lshlrev_b32_e32 v40, 16, v34
	v_lshlrev_b32_e32 v42, 16, v36
	v_and_b32_e32 v43, 0xffff0000, v36
	v_lshlrev_b32_e32 v36, 16, v37
	v_and_b32_e32 v37, 0xffff0000, v37
	v_pk_mul_f32 v[42:43], v[12:13], v[42:43]
	v_pk_mul_f32 v[36:37], v[14:15], v[36:37]
	v_and_b32_e32 v41, 0xffff0000, v34
	v_lshlrev_b32_e32 v34, 16, v35
	v_and_b32_e32 v35, 0xffff0000, v35
	v_lshlrev_b32_e32 v44, 16, v38
	v_and_b32_e32 v45, 0xffff0000, v38
	v_lshlrev_b32_e32 v38, 16, v39
	v_and_b32_e32 v39, 0xffff0000, v39
	v_pk_mul_f32 v[36:37], v[30:31], v[36:37] op_sel_hi:[0,1]
	v_pk_mul_f32 v[30:31], v[30:31], v[42:43] op_sel_hi:[0,1]
	v_pk_fma_f32 v[40:41], v[16:17], v[40:41], v[30:31]
	v_pk_fma_f32 v[30:31], v[18:19], v[34:35], v[36:37]
	v_pk_mul_f32 v[34:35], v[20:21], v[44:45]
	v_pk_mul_f32 v[36:37], v[22:23], v[38:39]
	v_lshl_add_u64 v[44:45], s[0:1], 0, v[24:25]
	v_pk_fma_f32 v[30:31], v[32:33], v[36:37], v[30:31] op_sel_hi:[0,1,1]
	v_pk_fma_f32 v[32:33], v[32:33], v[34:35], v[40:41] op_sel_hi:[0,1,1]
	v_lshl_add_u64 v[34:35], s[0:1], 0, v[26:27]
	v_add_co_u32_e32 v36, vcc, s2, v34
	s_mov_b32 s2, 0x25100000
	s_nop 0
	v_addc_co_u32_e32 v37, vcc, 0, v35, vcc
	v_add_co_u32_e32 v38, vcc, s2, v34
	s_nop 0
	s_nop 0
	v_addc_co_u32_e32 v39, vcc, 0, v35, vcc
	s_nop 0
	s_mov_b32 s2, 0x56400000
	v_add_co_u32_e32 v46, vcc, s2, v44
	s_mov_b32 s2, 0x56520000
	s_nop 0
	v_addc_co_u32_e32 v47, vcc, 0, v45, vcc
	v_add_co_u32_e32 v44, vcc, s2, v44
	s_nop 0
	s_nop 0
	v_addc_co_u32_e32 v45, vcc, 0, v45, vcc
	s_nop 0
	v_lshl_add_u64 v[24:25], v[24:25], 0, s[10:11]
	v_lshl_add_u64 v[26:27], v[26:27], 0, s[12:13]
	s_waitcnt vmcnt(4)
	v_lshlrev_b32_e32 v40, 16, v118
	v_and_b32_e32 v41, 0xffff0000, v118
	v_lshlrev_b32_e32 v36, 16, v119
	v_and_b32_e32 v37, 0xffff0000, v119
	s_waitcnt vmcnt(3)
; __device__ __forceinline__ unsigned pk2(float lo, float hi) { const f32x2 v = {lo, hi}; return __builtin_bit_cast(unsigned, __builtin_convertvector(v, bf2n_t_)); }
; __device__ __forceinline__ float red16s(float v) { v += dppf<0xB1, 0xF>(v); v += dppf<0x4E, 0xF>(v); v += dppf<0x141, 0xF>(v); v += dppf<0x140, 0xF>(v); return v; }
; __device__ __forceinline__ void phase_mixout(const Frame& F, ArgsRef A, int l, int nrows) {
;     ...
;             const float bs = BS[(size_t)m * 16 + hd] + BS[((size_t)MT + m) * 16 + hd];
;             const f32x4 o = y0 + y1;
;             const float mean = red16s((o.x + o.y) + (o.z + o.w)) * (1.f / 64.f); const f32x4 dv = o - mean;
;             const float var = red16s((dv.x * dv.x + dv.y * dv.y) + (dv.z * dv.z + dv.w * dv.w)) * (1.f / 64.f);
;             const f32x4 on = dv * (1.f / sqrtf(var + 64e-5f)) * lnw + lnb;
;             const v2u gw2 = *(const v2u*)(G + (size_t)m * 1024 + c0);
;             const f32x4 gv = (f32x4){bflo(gw2.x), bfhi(gw2.x), bflo(gw2.y), bfhi(gw2.y)};
;             const f32x4 res = (on + v * bs) * gv;
;             *(v2u*)(ORW + (size_t)m * ZA_LD + c0) = (v2u){pk2(res.x, res.y), pk2(res.z, res.w)};
	v_lshlrev_b32_e32 v42, 16, v120
	v_and_b32_e32 v43, 0xffff0000, v120
	v_lshlrev_b32_e32 v38, 16, v121
	v_and_b32_e32 v39, 0xffff0000, v121
	v_pk_add_f32 v[36:37], v[36:37], v[38:39]
	v_pk_add_f32 v[38:39], v[40:41], v[42:43]
	v_mov_b32_e32 v43, v37
	v_pk_mov_b32 v[40:41], v[38:39], v[36:37] op_sel:[1,0]
	v_mov_b32_e32 v42, v38
	v_pk_add_f32 v[40:41], v[40:41], v[42:43]
	s_waitcnt vmcnt(1)
	v_add_f32_e32 v44, v122, v123
	v_add_f32_e32 v40, v40, v41
	s_nop 1
	v_add_f32_dpp v40, v40, v40 quad_perm:[1,0,3,2] row_mask:0xf bank_mask:0xf bound_ctrl:1
	s_nop 1
	v_add_f32_dpp v40, v40, v40 quad_perm:[2,3,0,1] row_mask:0xf bank_mask:0xf bound_ctrl:1
	s_nop 1
	v_add_f32_dpp v40, v40, v40 row_half_mirror row_mask:0xf bank_mask:0xf bound_ctrl:1
	s_nop 1
	v_add_f32_dpp v40, v40, v40 row_mirror row_mask:0xf bank_mask:0xf bound_ctrl:1
	v_fmamk_f32 v39, v40, 0xbc800000, v39
	v_fmac_f32_e32 v38, 0xbc800000, v40
	v_fmamk_f32 v37, v40, 0xbc800000, v37
	v_fmac_f32_e32 v36, 0xbc800000, v40
	v_pk_mul_f32 v[40:41], v[36:37], v[36:37]
	v_pk_mul_f32 v[42:43], v[38:39], v[38:39]
	s_nop 0
	v_pk_mov_b32 v[46:47], v[42:43], v[40:41] op_sel:[1,0]
	v_mov_b32_e32 v43, v41
	v_pk_add_f32 v[40:41], v[46:47], v[42:43]
	s_nop 0
	v_add_f32_e32 v40, v40, v41
	v_mov_b32_e32 v41, 0x3a27c5ac
	s_nop 0
	v_add_f32_dpp v40, v40, v40 quad_perm:[1,0,3,2] row_mask:0xf bank_mask:0xf bound_ctrl:1
	s_nop 1
	v_add_f32_dpp v40, v40, v40 quad_perm:[2,3,0,1] row_mask:0xf bank_mask:0xf bound_ctrl:1
	s_nop 1
	v_add_f32_dpp v40, v40, v40 row_half_mirror row_mask:0xf bank_mask:0xf bound_ctrl:1
	s_nop 1
	v_add_f32_dpp v40, v40, v40 row_mirror row_mask:0xf bank_mask:0xf bound_ctrl:1
	v_fmamk_f32 v40, v40, 0x3c800000, v41
	v_cmp_gt_f32_e32 vcc, s73, v40
	v_mul_f32_e32 v41, 0x4f800000, v40
	s_nop 0
	v_cndmask_b32_e32 v40, v40, v41, vcc
	v_sqrt_f32_e32 v41, v40
	s_nop 0
	v_add_u32_e32 v42, -1, v41
	v_fma_f32 v43, -v42, v41, v40
	v_cmp_ge_f32_e64 s[2:3], 0, v43
	v_add_u32_e32 v43, 1, v41
	s_nop 0
	v_cndmask_b32_e64 v42, v41, v42, s[2:3]
	v_fma_f32 v41, -v43, v41, v40
	v_cmp_lt_f32_e64 s[2:3], 0, v41
	s_nop 1
	v_cndmask_b32_e64 v41, v42, v43, s[2:3]
	v_mul_f32_e32 v42, 0x37800000, v41
	v_cndmask_b32_e32 v41, v41, v42, vcc
	v_cmp_class_f32_e32 vcc, v40, v227
	s_nop 1
	v_cndmask_b32_e32 v40, v41, v40, vcc
	v_div_scale_f32 v41, s[2:3], v40, v40, 1.0
	v_rcp_f32_e32 v42, v41
	s_mov_b32 s2, 0x2bd00000
	v_fma_f32 v43, -v41, v42, 1.0
	v_fmac_f32_e32 v42, v43, v42
	v_div_scale_f32 v43, vcc, 1.0, v40, 1.0
	v_mul_f32_e32 v45, v43, v42
	v_fma_f32 v46, -v41, v45, v43
	v_fmac_f32_e32 v45, v46, v42
	v_fma_f32 v41, -v41, v45, v43
	v_div_fmas_f32 v41, v41, v42, v45
	v_add_co_u32_e32 v34, vcc, s2, v34
	v_div_fixup_f32 v40, v41, v40, 1.0
	s_nop 0
	v_addc_co_u32_e32 v35, vcc, 0, v35, vcc
	s_nop 0
	v_pk_mul_f32 v[38:39], v[38:39], v[40:41] op_sel_hi:[1,0]
	v_pk_mul_f32 v[36:37], v[36:37], v[40:41] op_sel_hi:[1,0]
	v_pk_fma_f32 v[38:39], v[4:5], v[38:39], v[8:9]
	v_pk_fma_f32 v[36:37], v[6:7], v[36:37], v[10:11]
	v_pk_fma_f32 v[32:33], v[44:45], v[32:33], v[38:39] op_sel_hi:[0,1,1]
	v_pk_fma_f32 v[30:31], v[44:45], v[30:31], v[36:37] op_sel_hi:[0,1,1]
	s_waitcnt vmcnt(0)
	v_lshlrev_b32_e32 v40, 16, v124
	v_and_b32_e32 v41, 0xffff0000, v124
	v_lshlrev_b32_e32 v34, 16, v125
	v_and_b32_e32 v35, 0xffff0000, v125
	v_pk_mul_f32 v[34:35], v[30:31], v[34:35]
	v_pk_mul_f32 v[30:31], v[32:33], v[40:41]
	v_lshl_add_u64 v[32:33], s[0:1], 0, v[0:1]
	v_cvt_pk_bf16_f32 v30, v30, v31
	v_cvt_pk_bf16_f32 v31, v34, v35
	v_lshl_add_u64 v[0:1], v[0:1], 0, s[8:9]
	global_store_dwordx2 v[32:33], v[30:31], off
	s_cbranch_scc0 .LBB0_906

; __device__ __forceinline__ unsigned pk2(float lo, float hi) { const f32x2 v = {lo, hi}; return __builtin_bit_cast(unsigned, __builtin_convertvector(v, bf2n_t_)); }
; __device__ __forceinline__ float fsilu(float x) { return x * __builtin_amdgcn_rcpf(1.0f + fexp(-x)); }
; __device__ __forceinline__ void phase_mixout(const Frame& F, ArgsRef A, int l, int nrows) {
;     ...
;         for (int it = gw; it < nrows * 4; it += NGW) {
;             const int m = it >> 2, h = it & 3;
;             const v4u ya = *(const v4u*)(YG + (size_t)m * 2048 + h * 512 + lane * 8), yb = *(const v4u*)(YG + ((size_t)MT + m) * 2048 + h * 512 + lane * 8);
;             f32x4 y0 = (f32x4){bflo(ya.x) + bflo(yb.x), bfhi(ya.x) + bfhi(yb.x), bflo(ya.y) + bflo(yb.y), bfhi(ya.y) + bfhi(yb.y)};
;             f32x4 y1 = (f32x4){bflo(ya.z) + bflo(yb.z), bfhi(ya.z) + bfhi(yb.z), bflo(ya.w) + bflo(yb.w), bfhi(ya.w) + bfhi(yb.w)};
;             const float ss = wave_sum((y0.x * y0.x + y0.y * y0.y) + (y0.z * y0.z + y0.w * y0.w) + (y1.x * y1.x + y1.y * y1.y) + (y1.z * y1.z + y1.w * y1.w));
;             const float rs = 1.f / sqrtf(ss * (1.f / 512.f) + 1e-5f);
;             const v4u gw4 = *(const v4u*)(ZG + (size_t)m * ZG_W + 4096 + h * 512 + lane * 8);
;             const f32x4 g0 = (f32x4){bflo(gw4.x), bfhi(gw4.x), bflo(gw4.y), bfhi(gw4.y)}, g1 = (f32x4){bflo(gw4.z), bfhi(gw4.z), bflo(gw4.w), bfhi(gw4.w)};
;             y0 = y0 * rs * nw0; y1 = y1 * rs * nw1;
;             v4u w; w.x = pk2(y0.x * fsilu(g0.x), y0.y * fsilu(g0.y)); w.y = pk2(y0.z * fsilu(g0.z), y0.w * fsilu(g0.w));
;             w.z = pk2(y1.x * fsilu(g1.x), y1.y * fsilu(g1.y)); w.w = pk2(y1.z * fsilu(g1.z), y1.w * fsilu(g1.w));
;             *(v4u*)(OGL + (size_t)m * ZA_LD + h * 512 + lane * 8) = w;
.LBB0_909:
	s_ashr_i32 s4, s6, 2
	s_ashr_i32 s5, s4, 31
	s_lshl_b64 s[2:3], s[4:5], 12
	s_add_u32 s2, s8, s2
	s_addc_u32 s3, s9, s3
	s_and_b32 s5, s13, 0x600
	s_lshl_b32 s5, s5, 1
	s_add_u32 s2, s2, s5
	s_addc_u32 s3, s3, 0
	v_lshl_add_u64 v[12:13], s[2:3], 0, v[0:1]
	s_mov_b32 s2, 0x4800000
	global_load_dwordx4 v[16:19], v[12:13], off
	v_add_co_u32_e32 v12, vcc, s2, v12
	s_nop 1
	v_addc_co_u32_e32 v13, vcc, 0, v13, vcc
	global_load_dwordx4 v[20:23], v[12:13], off
	s_mul_i32 s3, s4, 0x3000
	s_mul_hi_i32 s2, s4, 0x3000
	s_add_u32 s3, s0, s3
	s_addc_u32 s15, s1, s2
	s_add_u32 s2, s3, s5
	s_addc_u32 s3, s15, 0
	v_lshl_add_u64 v[104:105], s[2:3], 0, v[0:1]
	s_mov_b32 s2, 0x2e102000
	v_add_co_u32_e32 v104, vcc, s2, v104
	s_nop 1
	v_addc_co_u32_e32 v105, vcc, 0, v105, vcc
	global_load_dwordx4 v[108:111], v[104:105], off
	s_waitcnt vmcnt(1)
	v_lshlrev_b32_e32 v12, 16, v16
	v_and_b32_e32 v13, 0xffff0000, v16
	v_lshlrev_b32_e32 v14, 16, v20
	v_and_b32_e32 v15, 0xffff0000, v20
	v_pk_add_f32 v[12:13], v[12:13], v[14:15]
	v_lshlrev_b32_e32 v14, 16, v17
	v_and_b32_e32 v15, 0xffff0000, v17
	v_lshlrev_b32_e32 v16, 16, v21
	v_and_b32_e32 v17, 0xffff0000, v21
	v_pk_add_f32 v[14:15], v[14:15], v[16:17]
	v_lshlrev_b32_e32 v16, 16, v18
	v_and_b32_e32 v17, 0xffff0000, v18
	v_lshlrev_b32_e32 v20, 16, v22
	v_and_b32_e32 v21, 0xffff0000, v22
	v_pk_add_f32 v[16:17], v[16:17], v[20:21]
	v_lshlrev_b32_e32 v18, 16, v19
	v_and_b32_e32 v19, 0xffff0000, v19
	v_lshlrev_b32_e32 v20, 16, v23
	v_and_b32_e32 v21, 0xffff0000, v23
	v_pk_add_f32 v[18:19], v[18:19], v[20:21]
	v_pk_mul_f32 v[20:21], v[12:13], v[12:13]
	v_pk_mul_f32 v[22:23], v[14:15], v[14:15]
	v_pk_mul_f32 v[24:25], v[16:17], v[16:17]
	v_add_f32_e32 v22, v22, v23
	v_add_f32_e32 v20, v20, v21
	v_pk_mul_f32 v[26:27], v[18:19], v[18:19]
	v_add_f32_e32 v20, v20, v22
	v_add_f32_e32 v21, v24, v25
	v_add_f32_e32 v26, v26, v27
	v_add_f32_e32 v20, v21, v20
	v_add_f32_e32 v20, v26, v20
	v_mov_b32_e32 v21, v2
	s_nop 0
	v_add_f32_dpp v20, v20, v20 quad_perm:[1,0,3,2] row_mask:0xf bank_mask:0xf bound_ctrl:1
	s_nop 1
	v_add_f32_dpp v20, v20, v20 quad_perm:[2,3,0,1] row_mask:0xf bank_mask:0xf bound_ctrl:1
	s_nop 1
	v_add_f32_dpp v20, v20, v20 row_half_mirror row_mask:0xf bank_mask:0xf bound_ctrl:1
	s_nop 1
	v_add_f32_dpp v20, v20, v20 row_mirror row_mask:0xf bank_mask:0xf bound_ctrl:1
	s_nop 1
	v_mov_b32_dpp v21, v20 row_bcast:15 row_mask:0xa bank_mask:0xf
	v_add_f32_e32 v20, v20, v21
	v_mov_b32_e32 v21, v2
	s_nop 1
	v_mov_b32_dpp v21, v20 row_bcast:31 row_mask:0xc bank_mask:0xf
	v_add_f32_e32 v20, v20, v21
	s_nop 0
	v_readlane_b32 s2, v20, 63
	v_mov_b32_e32 v20, 0x3b000000
	s_nop 0
	v_fma_f32 v20, s2, v20, v225
	v_cmp_gt_f32_e32 vcc, s73, v20
	v_mul_f32_e32 v21, 0x4f800000, v20
	s_nop 0
	v_cndmask_b32_e32 v20, v20, v21, vcc
	v_sqrt_f32_e32 v21, v20
	s_nop 0
	v_add_u32_e32 v22, -1, v21
	v_fma_f32 v23, -v22, v21, v20
	v_cmp_ge_f32_e64 s[2:3], 0, v23
	v_add_u32_e32 v23, 1, v21
	s_nop 0
	v_cndmask_b32_e64 v22, v21, v22, s[2:3]
	v_fma_f32 v21, -v23, v21, v20
	v_cmp_lt_f32_e64 s[2:3], 0, v21
	s_nop 1
	v_cndmask_b32_e64 v21, v22, v23, s[2:3]
	v_mul_f32_e32 v22, 0x37800000, v21
	v_cndmask_b32_e32 v21, v21, v22, vcc
	v_cmp_class_f32_e32 vcc, v20, v227
	s_nop 1
	v_cndmask_b32_e32 v20, v21, v20, vcc
	v_div_scale_f32 v21, s[2:3], v20, v20, 1.0
	v_rcp_f32_e32 v22, v21
	s_mul_i32 s3, s4, 0x3000
	s_mul_hi_i32 s2, s4, 0x3000
	s_add_u32 s3, s0, s3
	v_fma_f32 v23, -v21, v22, 1.0
	v_fmac_f32_e32 v22, v23, v22
	v_div_scale_f32 v23, vcc, 1.0, v20, 1.0
	v_mul_f32_e32 v24, v23, v22
	v_fma_f32 v25, -v21, v24, v23
	v_fmac_f32_e32 v24, v25, v22
	s_addc_u32 s15, s1, s2
	v_fma_f32 v21, -v21, v24, v23
	s_add_u32 s2, s3, s5
	v_div_fmas_f32 v21, v21, v22, v24
	s_addc_u32 s3, s15, 0
	v_div_fixup_f32 v24, v21, v20, 1.0
	v_lshl_add_u64 v[20:21], s[2:3], 0, v[0:1]
	s_mov_b32 s2, 0x2e102000
	v_add_co_u32_e32 v20, vcc, s2, v20
	v_pk_mul_f32 v[12:13], v[12:13], v[24:25] op_sel_hi:[1,0]
	s_nop 0
	v_addc_co_u32_e32 v21, vcc, 0, v21, vcc
	s_nop 0
	v_pk_mul_f32 v[14:15], v[14:15], v[24:25] op_sel_hi:[1,0]
	v_pk_mul_f32 v[16:17], v[16:17], v[24:25] op_sel_hi:[1,0]
	v_pk_mul_f32 v[18:19], v[18:19], v[24:25] op_sel_hi:[1,0]
	v_pk_mul_f32 v[12:13], v[8:9], v[12:13]
	v_pk_mul_f32 v[14:15], v[10:11], v[14:15]
	v_pk_mul_f32 v[16:17], v[4:5], v[16:17]
	s_mul_i32 s3, s4, 0x2400
	s_mul_hi_i32 s2, s4, 0x2400
	s_add_u32 s3, s10, s3
	s_addc_u32 s4, s11, s2
	v_pk_mul_f32 v[18:19], v[6:7], v[18:19]
	s_add_u32 s2, s3, s5
	s_addc_u32 s3, s4, 0
	s_add_i32 s6, s6, s12
	s_add_i32 s13, s13, s14
	s_cmp_lt_i32 s6, s7
	s_waitcnt vmcnt(0)
	v_lshlrev_b32_e32 v24, 16, v108
	v_and_b32_e32 v25, 0xffff0000, v108
	v_mul_f32_e32 v20, 0xbfb8aa3b, v24
	v_exp_f32_e32 v20, v20
	s_nop 0
	v_add_f32_e32 v20, 1.0, v20
	v_rcp_f32_e32 v26, v20
	v_mul_f32_e32 v20, 0xbfb8aa3b, v25
	v_exp_f32_e32 v20, v20
	s_nop 0
	v_add_f32_e32 v20, 1.0, v20
	v_rcp_f32_e32 v27, v20
	v_lshlrev_b32_e32 v20, 16, v109
	v_and_b32_e32 v21, 0xffff0000, v109
	v_pk_mul_f32 v[24:25], v[26:27], v[24:25]
	s_nop 0
	v_pk_mul_f32 v[12:13], v[12:13], v[24:25]
	s_nop 0
	v_cvt_pk_bf16_f32 v12, v12, v13
	v_mul_f32_e32 v13, 0xbfb8aa3b, v20
	v_exp_f32_e32 v13, v13
	s_nop 0
	v_add_f32_e32 v13, 1.0, v13
	v_rcp_f32_e32 v24, v13
	v_mul_f32_e32 v13, 0xbfb8aa3b, v21
	v_exp_f32_e32 v13, v13
	s_nop 0
	v_add_f32_e32 v13, 1.0, v13
	v_rcp_f32_e32 v25, v13
	s_nop 0
	v_pk_mul_f32 v[20:21], v[24:25], v[20:21]
	s_nop 0
	v_pk_mul_f32 v[14:15], v[14:15], v[20:21]
	s_nop 0
	v_cvt_pk_bf16_f32 v13, v14, v15
	v_lshlrev_b32_e32 v14, 16, v110
	v_and_b32_e32 v15, 0xffff0000, v110
	v_mul_f32_e32 v20, 0xbfb8aa3b, v14
	v_mul_f32_e32 v21, 0xbfb8aa3b, v15
	v_exp_f32_e32 v20, v20
	v_exp_f32_e32 v21, v21
	v_add_f32_e32 v20, 1.0, v20
	v_add_f32_e32 v21, 1.0, v21
	v_rcp_f32_e32 v20, v20
	v_rcp_f32_e32 v21, v21
	s_nop 0
	v_pk_mul_f32 v[14:15], v[20:21], v[14:15]
	s_nop 0
	v_pk_mul_f32 v[14:15], v[16:17], v[14:15]
	v_lshlrev_b32_e32 v16, 16, v111
	v_cvt_pk_bf16_f32 v14, v14, v15
	v_mul_f32_e32 v15, 0xbfb8aa3b, v16
	v_exp_f32_e32 v15, v15
	v_and_b32_e32 v17, 0xffff0000, v111
	v_add_f32_e32 v15, 1.0, v15
	v_rcp_f32_e32 v20, v15
	v_mul_f32_e32 v15, 0xbfb8aa3b, v17
	v_exp_f32_e32 v15, v15
	s_nop 0
	v_add_f32_e32 v15, 1.0, v15
	v_rcp_f32_e32 v21, v15
	s_nop 0
	v_pk_mul_f32 v[16:17], v[20:21], v[16:17]
	s_nop 0
	v_pk_mul_f32 v[16:17], v[18:19], v[16:17]
	s_nop 0
	v_cvt_pk_bf16_f32 v15, v16, v17
	v_lshl_add_u64 v[16:17], s[2:3], 0, v[0:1]
	global_store_dwordx4 v[16:17], v[12:15], off
	s_cbranch_scc1 .LBB0_909
